# SGU unit loop: loop-invariant W fragments loaded once per workgroup, parked in wave-private LDS, re-read per unit with ds_read_b128 instead of row-per-lane global loads
# speedup vs baseline: 1.0041x; 1.0041x over previous
; #define LAS __attribute__((address_space(3)))
; DI void sgu_load(const Params& p, int uid, int tid, SguRegs& R) {
;     ...
;     const int ib = w & 3, iloc = 32 * ib + r32;
;     R.bsv = p.in[22][g * 128 + iloc];
; }
; DI void sgu_unit(const Params& p, LAS unsigned char* lds, int uid, int tid, const SguRegs& C, bool has_next, int uid_next, SguRegs& R) {
;     const int b = uid >> 7, ch = (uid >> 2) & 31, g = uid & 3;
;     const int lane = tid & 63, w = __builtin_amdgcn_readfirstlane(tid >> 6), r32 = lane & 31, h = lane >> 5;
;     bf16_t* CAT = (bf16_t*)(p.ws + WS_CAT);
;     const float* sw = p.in[21];
;     const size_t r0 = (size_t)b * SEQ + ch * 128;
;     const int ib = w & 3, dh = w >> 2, iloc = 32 * ib + r32;
;     const size_t row = r0 + iloc;
;     const float* Wrow = sw + ((size_t)g * 128 + iloc) * 128 + 8 * h;
;     f32x4 wv[8][2];
; #pragma unroll
;     for (int js = 0; js < 8; ++js) { if (js <= 2 * ib + 1) { wv[js][0] = *(const f32x4*)(Wrow + 16 * js); wv[js][1] = *(const f32x4*)(Wrow + 16 * js + 4); } else { wv[js][0] = (f32x4){0.f, 0.f, 0.f, 0.f}; wv[js][1] = wv[js][0]; } }
; DI void sgu_all(const Params& p, LAS unsigned char* lds, int first, int stride) {
;     int tid_ = threadIdx.x; asm volatile("" : "+v"(tid_));
;     const int tid = tid_;
;     __syncthreads();
;     { LAS float* lnp = (LAS float*)(lds + SG_LN); lnp[tid] = p.in[19][tid]; lnp[512 + tid] = p.in[20][tid]; }
;     if (first >= 1024) { __syncthreads(); return; }
;     SguRegs R; sgu_load(p, first, tid, R);
;     for (int uid = first; uid < 1024; uid += stride) {
;         const SguRegs C = R;
;         sgu_unit(p, lds, uid, tid, C, uid + stride < 1024, uid + stride, R);
.LBB0_1235:
	s_waitcnt lgkmcnt(0)
	v_ashrrev_i32_e32 v149, 31, v148
	v_lshlrev_b64 v[2:3], 2, v[148:149]
	v_lshl_add_u64 v[4:5], s[42:43], 0, v[2:3]
	v_lshl_add_u64 v[2:3], s[44:45], 0, v[2:3]
	s_barrier
	global_load_dword v4, v[4:5], off
	v_readlane_b32 s6, v247, 3
	global_load_dword v2, v[2:3], off
	v_readlane_b32 s7, v247, 4
	s_mov_b32 s5, 0
	s_mov_b64 s[0:1], -1
	s_and_b64 vcc, exec, s[6:7]
	v_lshl_add_u32 v3, v148, 2, 0
	s_waitcnt vmcnt(0)
	ds_write2st64_b32 v3, v4, v2 offset0:192 offset1:200
	s_cbranch_vccz .LBB0_1265
	v_ashrrev_i32_e32 v146, 2, v148
	v_readlane_b32 s10, v247, 9
	v_ashrrev_i32_e32 v147, 31, v146
	v_readlane_b32 s11, v247, 10
	v_mov_b32_e32 v151, 0
	v_mov_b32_e32 v153, v151
	v_lshl_add_u64 v[2:3], s[10:11], 0, v[146:147]
	v_readlane_b32 s10, v247, 7
	v_lshlrev_b64 v[4:5], 6, v[2:3]
	v_readlane_b32 s11, v247, 8
	v_lshlrev_b64 v[2:3], 10, v[2:3]
	s_movk_i32 s1, 0x60
	v_lshl_add_u64 v[14:15], s[10:11], 0, v[4:5]
	v_readlane_b32 s10, v247, 11
	v_lshlrev_b32_e32 v4, 5, v148
	v_readlane_b32 s11, v247, 12
	v_and_b32_e32 v16, 0x60, v4
	v_lshlrev_b32_e32 v152, 1, v16
	v_lshl_add_u64 v[2:3], s[10:11], 0, v[2:3]
	v_lshl_add_u64 v[18:19], v[2:3], 0, v[152:153]
	global_load_dwordx4 v[30:33], v[14:15], off offset:48
	global_load_dwordx4 v[26:29], v[14:15], off offset:32
	global_load_dwordx4 v[138:141], v[14:15], off offset:16
	global_load_dwordx4 v[142:145], v[14:15], off
	global_load_dwordx4 v[2:5], v[18:19], off offset:48
	global_load_dwordx4 v[6:9], v[18:19], off offset:32
	global_load_dwordx4 v[10:13], v[18:19], off offset:16
	global_load_dwordx4 v[22:25], v[18:19], off
	v_and_b32_e32 v149, 31, v148
	v_lshrrev_b32_e32 v14, 1, v148
	v_and_or_b32 v153, v14, s1, v149
	v_readlane_b32 s1, v247, 5
	s_lshl_b32 s0, s85, 14
	s_lshl_b32 s6, s84, 1
	v_or_b32_e32 v15, s1, v153
	v_lshlrev_b32_e32 v15, 2, v15
	global_load_dword v156, v15, s[48:49]
	v_lshrrev_b32_e32 v15, 2, v148
	v_and_b32_e32 v157, 8, v15
	s_movk_i32 s1, 0x140
	v_and_b32_e32 v15, 11, v15
	v_mad_u32_u24 v165, v15, s1, 0
	v_lshlrev_b32_e32 v15, 2, v148
	v_and_b32_e32 v15, 12, v15
	v_and_b32_e32 v154, 16, v14
	v_mul_lo_u32 v14, v146, s1
	v_and_or_b32 v166, v148, 16, v15
	v_or_b32_e32 v15, s84, v16
	s_add_u32 s8, s50, s6
	v_add_u32_e32 v164, 0, v14
	v_or_b32_e32 v14, 16, v152
	v_or_b32_e32 v17, 32, v152
	v_or_b32_e32 v18, 48, v152
	v_lshl_add_u32 v229, v15, 2, 0
	v_add_u32_e32 v15, s84, v16
	v_lshlrev_b32_e32 v150, 2, v157
	s_addc_u32 s9, s51, 0
	v_mov_b32_e32 v155, v151
	v_or_b32_e32 v167, 4, v157
	v_or_b32_e32 v168, 5, v157
	v_or_b32_e32 v169, 2, v157
	v_or_b32_e32 v170, 6, v157
	v_or_b32_e32 v171, 3, v157
	v_or_b32_e32 v172, 7, v157
	v_or_b32_e32 v173, 16, v157
	v_or_b32_e32 v174, 20, v157
	v_or_b32_e32 v175, 17, v157
	v_or_b32_e32 v176, 21, v157
	v_or_b32_e32 v177, 18, v157
	v_or_b32_e32 v178, 22, v157
	v_or_b32_e32 v179, 19, v157
	v_or_b32_e32 v180, 23, v157
	v_or_b32_e32 v181, 32, v157
	v_or_b32_e32 v182, 36, v157
	v_or_b32_e32 v183, 33, v157
	v_or_b32_e32 v184, 37, v157
	v_or_b32_e32 v185, 34, v157
	v_or_b32_e32 v186, 38, v157
	v_or_b32_e32 v187, 35, v157
	v_or_b32_e32 v188, 39, v157
	v_or_b32_e32 v189, 48, v157
	v_or_b32_e32 v190, 52, v157
	v_or_b32_e32 v191, 49, v157
	v_or_b32_e32 v192, 53, v157
	v_or_b32_e32 v193, 50, v157
	v_or_b32_e32 v194, 54, v157
	v_or_b32_e32 v195, 51, v157
	v_or_b32_e32 v196, 55, v157
	v_or_b32_e32 v197, 64, v157
	v_or_b32_e32 v198, 0x44, v157
	v_or_b32_e32 v199, 0x41, v157
	v_or_b32_e32 v200, 0x45, v157
	v_or_b32_e32 v201, 0x42, v157
	v_or_b32_e32 v202, 0x46, v157
	v_or_b32_e32 v203, 0x43, v157
	v_or_b32_e32 v204, 0x47, v157
	v_or_b32_e32 v205, 0x50, v157
	v_or_b32_e32 v206, 0x54, v157
	v_or_b32_e32 v207, 0x51, v157
	v_or_b32_e32 v208, 0x55, v157
	v_or_b32_e32 v209, 0x52, v157
	v_or_b32_e32 v210, 0x56, v157
	v_or_b32_e32 v211, 0x53, v157
	v_or_b32_e32 v212, 0x57, v157
	v_or_b32_e32 v213, 0x60, v157
	v_or_b32_e32 v214, 0x64, v157
	v_or_b32_e32 v215, 0x61, v157
	v_or_b32_e32 v216, 0x65, v157
	v_or_b32_e32 v217, 0x62, v157
	v_or_b32_e32 v218, 0x66, v157
	v_or_b32_e32 v219, 0x63, v157
	v_or_b32_e32 v220, 0x67, v157
	v_or_b32_e32 v221, 0x70, v157
	v_or_b32_e32 v222, 0x74, v157
	v_or_b32_e32 v223, 0x71, v157
	v_or_b32_e32 v224, 0x75, v157
	v_or_b32_e32 v225, 0x72, v157
	v_or_b32_e32 v226, 0x76, v157
	v_or_b32_e32 v227, 0x73, v157
	v_or_b32_e32 v228, 0x77, v157
	v_lshl_add_u32 v230, v15, 2, 0
	v_lshl_add_u64 v[158:159], s[46:47], 0, v[150:151]
	s_lshl_b32 s11, s0, 2
	v_lshlrev_b32_e32 v160, 1, v16
	s_mov_b32 s10, 0x3b000000
	s_mov_b32 s12, 0x800000
	v_add_u32_e32 v231, v164, v14
	v_add_u32_e32 v232, v164, v17
	v_add_u32_e32 v233, v164, v18
	s_mov_b64 s[18:19], 0x11c00400
	s_mov_b32 s13, 0x11c00000
	s_mov_b32 s7, s5
	s_mov_b32 s4, s2
	v_readfirstlane_b32 s100, v148
	s_bfe_u32 s98, s100, 0x20006
	s_bfe_u32 s101, s100, 0x10008
	s_mul_i32 s101, s101, 0xa000
	s_add_i32 s99, s98, 1
	s_mul_i32 s99, s99, s98
	s_lshl_b32 s99, s99, 11
	s_add_i32 s99, s99, s101
	s_add_i32 s99, s99, 0xd000
	v_and_b32_e32 v248, 63, v148
	v_lshl_add_u32 v248, v248, 4, s99
	v_lshl_or_b32 v250, s98, 5, v149
	v_lshl_or_b32 v250, v250, 9, s11
	v_mov_b32_e32 v251, 0
	v_lshl_add_u64 v[250:251], v[158:159], 0, v[250:251]
	global_load_dwordx4 v[14:17], v[250:251], off offset:16
	global_load_dwordx4 v[18:21], v[250:251], off
	global_load_dwordx4 v[130:133], v[250:251], off offset:80
	global_load_dwordx4 v[134:137], v[250:251], off offset:64
	s_cmp_eq_u32 s98, 0
	s_cbranch_scc1 .Lmy_wc_ld_done
	global_load_dwordx4 v[118:121], v[250:251], off offset:144
	global_load_dwordx4 v[126:129], v[250:251], off offset:128
	global_load_dwordx4 v[110:113], v[250:251], off offset:208
	global_load_dwordx4 v[122:125], v[250:251], off offset:192
	s_cmp_lt_u32 s98, 2
	s_cbranch_scc1 .Lmy_wc_ld_done
	global_load_dwordx4 v[94:97], v[250:251], off offset:272
	global_load_dwordx4 v[114:117], v[250:251], off offset:256
	global_load_dwordx4 v[102:105], v[250:251], off offset:336
	global_load_dwordx4 v[106:109], v[250:251], off offset:320
	s_cmp_lg_u32 s98, 3
	s_cbranch_scc1 .Lmy_wc_ld_done
	global_load_dwordx4 v[78:81], v[250:251], off offset:384
	global_load_dwordx4 v[98:101], v[250:251], off offset:400
	global_load_dwordx4 v[90:93], v[250:251], off offset:448
	global_load_dwordx4 v[86:89], v[250:251], off offset:464
; DI void sgu_unit(const Params& p, LAS unsigned char* lds, int uid, int tid, const SguRegs& C, bool has_next, int uid_next, SguRegs& R) {
;     ...
;     f32x4 wv[8][2];
; #pragma unroll
;     for (int js = 0; js < 8; ++js) { if (js <= 2 * ib + 1) { wv[js][0] = *(const f32x4*)(Wrow + 16 * js); wv[js][1] = *(const f32x4*)(Wrow + 16 * js + 4); } else { wv[js][0] = (f32x4){0.f, 0.f, 0.f, 0.f}; wv[js][1] = wv[js][0]; } }
.Lmy_wc_ld_done:
	s_waitcnt vmcnt(0)
	ds_write_b128 v248, v[14:17]
	ds_write_b128 v248, v[18:21] offset:1024
	ds_write_b128 v248, v[130:133] offset:2048
	ds_write_b128 v248, v[134:137] offset:3072
	s_cmp_eq_u32 s98, 0
	s_cbranch_scc1 .Lmy_wc_wr_done
	ds_write_b128 v248, v[118:121] offset:4096
	ds_write_b128 v248, v[126:129] offset:5120
	ds_write_b128 v248, v[110:113] offset:6144
	ds_write_b128 v248, v[122:125] offset:7168
	s_cmp_lt_u32 s98, 2
	s_cbranch_scc1 .Lmy_wc_wr_done
	ds_write_b128 v248, v[94:97] offset:8192
	ds_write_b128 v248, v[114:117] offset:9216
	ds_write_b128 v248, v[102:105] offset:10240
	ds_write_b128 v248, v[106:109] offset:11264
	s_cmp_lg_u32 s98, 3
	s_cbranch_scc1 .Lmy_wc_wr_done
	ds_write_b128 v248, v[78:81] offset:12288
	ds_write_b128 v248, v[98:101] offset:13312
	ds_write_b128 v248, v[90:93] offset:14336
	ds_write_b128 v248, v[86:89] offset:15360
.Lmy_wc_wr_done:
	s_waitcnt lgkmcnt(0)
	s_branch .LBB0_1238

; DI void sgu_unit(const Params& p, LAS unsigned char* lds, int uid, int tid, const SguRegs& C, bool has_next, int uid_next, SguRegs& R) {
;     ...
;     const float* Wrow = sw + ((size_t)g * 128 + iloc) * 128 + 8 * h;
;     f32x4 wv[8][2];
; #pragma unroll
;     for (int js = 0; js < 8; ++js) { if (js <= 2 * ib + 1) { wv[js][0] = *(const f32x4*)(Wrow + 16 * js); wv[js][1] = *(const f32x4*)(Wrow + 16 * js + 4); } else { wv[js][0] = (f32x4){0.f, 0.f, 0.f, 0.f}; wv[js][1] = wv[js][0]; } }
;     const bf16_t* Ub = (const bf16_t*)(p.ws + WS_A + 3 * SUB);
;     u32x4 uw[4];
;     { const unsigned char* ub = (const unsigned char*)(Ub + row * MW + g * 128 + 64 * dh) + (h ? 16 : 0);
; #pragma unroll
;       for (int kk = 0; kk < 4; ++kk) uw[kk] = *(const u32x4*)(ub + 32 * kk); }
;     if (has_next) sgu_load(p, uid_next, tid, R);
.LBB0_1238:
	v_readfirstlane_b32 s22, v148
	s_bfe_u32 s0, s22, 0x20006
	v_lshl_or_b32 v234, s0, 5, v149
	v_lshl_or_b32 v150, v234, 9, s11
	v_lshl_add_u64 v[34:35], v[158:159], 0, v[150:151]
	ds_read_b128 v[14:17], v248
	ds_read_b128 v[18:21], v248 offset:1024
	ds_read_b128 v[130:133], v248 offset:2048
	ds_read_b128 v[134:137], v248 offset:3072
	s_cmp_lg_u32 s0, 0
	s_cselect_b64 s[42:43], -1, 0
	s_cmp_eq_u32 s0, 0
	v_mov_b32_e32 v118, 0
	v_mov_b32_e32 v119, 0
	v_mov_b32_e32 v120, 0
	v_mov_b32_e32 v121, 0
	v_mov_b32_e32 v126, 0
	v_mov_b32_e32 v127, 0
	v_mov_b32_e32 v128, 0
	v_mov_b32_e32 v129, 0
	s_cbranch_scc1 .LBB0_1240
	ds_read_b128 v[118:121], v248 offset:4096
	ds_read_b128 v[126:129], v248 offset:5120
.LBB0_1240:
	s_lshl_b32 s1, s0, 1
	s_or_b32 s1, s1, 1
	s_cmp_gt_u32 s1, 2
	v_mov_b32_e32 v94, 0
	s_cselect_b64 s[40:41], -1, 0
	s_cmp_lt_u32 s1, 3
	v_mov_b32_e32 v110, 0
	v_mov_b32_e32 v111, 0
	v_mov_b32_e32 v112, 0
	v_mov_b32_e32 v113, 0
	v_mov_b32_e32 v122, 0
	v_mov_b32_e32 v123, 0
	v_mov_b32_e32 v124, 0
	v_mov_b32_e32 v125, 0
	s_cbranch_scc1 .LBB0_1242
	ds_read_b128 v[110:113], v248 offset:6144
	ds_read_b128 v[122:125], v248 offset:7168
.LBB0_1242:
	s_cmp_gt_u32 s0, 1
	s_cselect_b64 s[38:39], -1, 0
	s_cmp_lt_u32 s0, 2
	v_mov_b32_e32 v95, 0
	v_mov_b32_e32 v96, 0
	v_mov_b32_e32 v97, 0
	v_mov_b32_e32 v114, 0
	v_mov_b32_e32 v115, 0
	v_mov_b32_e32 v116, 0
	v_mov_b32_e32 v117, 0
	s_cbranch_scc1 .LBB0_1244
	ds_read_b128 v[94:97], v248 offset:8192
	ds_read_b128 v[114:117], v248 offset:9216
.LBB0_1244:
	s_cmp_gt_u32 s1, 4
	v_mov_b32_e32 v78, 0
	s_cselect_b64 s[36:37], -1, 0
	s_cmp_lt_u32 s1, 5
	v_mov_b32_e32 v102, 0
	v_mov_b32_e32 v103, 0
	v_mov_b32_e32 v104, 0
	v_mov_b32_e32 v105, 0
	v_mov_b32_e32 v106, 0
	v_mov_b32_e32 v107, 0
	v_mov_b32_e32 v108, 0
	v_mov_b32_e32 v109, 0
	s_cbranch_scc1 .LBB0_1246
	ds_read_b128 v[102:105], v248 offset:10240
	ds_read_b128 v[106:109], v248 offset:11264
.LBB0_1246:
	s_cmp_eq_u32 s0, 3
	s_cselect_b64 s[20:21], -1, 0
	s_cmp_lg_u32 s0, 3
	v_mov_b32_e32 v79, 0
	v_mov_b32_e32 v80, 0
	v_mov_b32_e32 v81, 0
	v_mov_b32_e32 v98, 0
	v_mov_b32_e32 v99, 0
	v_mov_b32_e32 v100, 0
	v_mov_b32_e32 v101, 0
	s_cbranch_scc1 .LBB0_1248
	ds_read_b128 v[78:81], v248 offset:12288
	ds_read_b128 v[98:101], v248 offset:13312
.LBB0_1248:
	v_cndmask_b32_e64 v36, 0, 1, s[20:21]
	v_mov_b32_e32 v90, 0
	v_cmp_ne_u32_e64 s[0:1], 1, v36
	s_andn2_b64 vcc, exec, s[20:21]
	v_mov_b32_e32 v91, 0
	v_mov_b32_e32 v92, 0
	v_mov_b32_e32 v93, 0
	v_mov_b32_e32 v86, 0
	v_mov_b32_e32 v87, 0
	v_mov_b32_e32 v88, 0
	v_mov_b32_e32 v89, 0
	s_cbranch_vccnz .LBB0_1250
	ds_read_b128 v[90:93], v248 offset:14336
	ds_read_b128 v[86:89], v248 offset:15360

; #define LAS __attribute__((address_space(3)))
; DI u32x4 pk8(f32x4 a, f32x4 b) { u32x4 w; w.x = pk2(a[0], a[1]); w.y = pk2(a[2], a[3]); w.z = pk2(b[0], b[1]); w.w = pk2(b[2], b[3]); return w; }
; DI void unpack8(const u32x4 w, float (&f)[8]) { f[0] = bflo(w.x); f[1] = bfhi(w.x); f[2] = bflo(w.y); f[3] = bfhi(w.y); f[4] = bflo(w.z); f[5] = bfhi(w.z); f[6] = bflo(w.w); f[7] = bfhi(w.w); }
; DI void sgu_unit(const Params& p, LAS unsigned char* lds, int uid, int tid, const SguRegs& C, bool has_next, int uid_next, SguRegs& R) {
;     ...
;     {
;         const int srow = tid >> 2, qt = tid & 3;
;         const f32x4 a0 = C.st[0], a1 = C.st[1], a2 = C.st[2], a3 = C.st[3];
;         const float s1 = (a0[0] + a0[2]) + (a1[0] + a1[2]) + (a2[0] + a2[2]) + (a3[0] + a3[2]);
;         const float s2 = (a0[1] + a0[3]) + (a1[1] + a1[3]) + (a2[1] + a2[3]) + (a3[1] + a3[3]);
;         const float mean = s1 * (1.0f / 512.0f), var = s2 * (1.0f / 512.0f) - mean * mean, rstd = rsqrtf(fmaxf(var, 0.f) + 1e-5f);
;         const LAS float* lnp = (const LAS float*)(lds + SG_LN);
; #pragma unroll
;         for (int i = 0; i < 4; ++i) {
;             const int c8 = qt * 32 + i * 8, ca = g * 128 + c8;
;             float f[8]; unpack8(C.sv[i], f);
;             const f32x4 g0 = *(const LAS f32x4*)(lnp + ca), g1 = *(const LAS f32x4*)(lnp + ca + 4), b0 = *(const LAS f32x4*)(lnp + 512 + ca), b1 = *(const LAS f32x4*)(lnp + 512 + ca + 4);
;             f32x4 x0, x1;
; #pragma unroll
;             for (int k = 0; k < 4; ++k) { x0[k] = (f[k] - mean) * rstd * g0[k] + b0[k]; x1[k] = (f[4 + k] - mean) * rstd * g1[k] + b1[k]; }
;             *(LAS u32x4*)(lds + srow * SG_STR + c8 * 2) = pk8(x0, x1);
;         }
;     }
.LBB0_1252:
	v_mov_b32_e32 v236, v138
	v_mov_b32_e32 v237, v142
	v_mov_b32_e32 v238, v140
	v_mov_b32_e32 v239, v144
	v_mov_b32_e32 v142, v139
	v_mov_b32_e32 v144, v141
	v_pk_add_f32 v[236:237], v[236:237], v[238:239]
	v_mov_b32_e32 v238, v30
	v_mov_b32_e32 v239, v26
	v_mov_b32_e32 v240, v32
	v_mov_b32_e32 v241, v28
	v_pk_add_f32 v[138:139], v[142:143], v[144:145]
	v_pk_add_f32 v[238:239], v[238:239], v[240:241]
	v_pk_add_f32 v[138:139], v[138:139], v[138:139] op_sel:[0,1] op_sel_hi:[1,0]
	v_pk_mov_b32 v[26:27], v[26:27], v[236:237] op_sel:[1,0]
	v_mov_b32_e32 v236, v29
	v_pk_add_f32 v[26:27], v[26:27], v[236:237]
	v_mov_b32_e32 v139, v239
	v_add_f32_e32 v28, v31, v33
	v_pk_add_f32 v[26:27], v[138:139], v[26:27]
	v_mov_b32_e32 v29, v238
	v_pk_add_f32 v[26:27], v[28:29], v[26:27]
	s_waitcnt lgkmcnt(0)
	v_pk_mul_f32 v[236:237], v[26:27], s[10:11] op_sel_hi:[1,0]
	s_barrier
	v_fma_f32 v26, -v237, v237, v236
	v_max_f32_e32 v26, 0, v26
	v_add_f32_e32 v26, 0x3727c5ac, v26
	v_mul_f32_e32 v27, 0x4b800000, v26
	v_cmp_gt_f32_e32 vcc, s12, v26
	v_lshlrev_b32_e32 v240, 16, v22
	s_nop 0
	v_cndmask_b32_e32 v26, v26, v27, vcc
	v_rsq_f32_e32 v26, v26
	v_and_b32_e32 v241, 0xffff0000, v22
	v_lshlrev_b32_e32 v22, 16, v23
	v_and_b32_e32 v23, 0xffff0000, v23
	v_mul_f32_e32 v27, 0x45800000, v26
	v_cndmask_b32_e32 v238, v26, v27, vcc
	ds_read_b128 v[26:29], v229 offset:49152
	ds_read_b128 v[30:33], v229 offset:49168
	ds_read_b128 v[138:141], v229 offset:51200
	ds_read_b128 v[142:145], v229 offset:51216
	v_pk_add_f32 v[240:241], v[240:241], v[236:237] op_sel:[0,1] neg_lo:[0,1] neg_hi:[0,1]
	v_pk_add_f32 v[22:23], v[22:23], v[236:237] op_sel:[0,1] neg_lo:[0,1] neg_hi:[0,1]
	v_pk_mul_f32 v[240:241], v[240:241], v[238:239] op_sel_hi:[1,0]
	v_pk_mul_f32 v[22:23], v[22:23], v[238:239] op_sel_hi:[1,0]
	s_waitcnt lgkmcnt(1)
	v_pk_fma_f32 v[26:27], v[240:241], v[26:27], v[138:139]
	v_lshlrev_b32_e32 v138, 16, v24
	v_and_b32_e32 v139, 0xffff0000, v24
	v_pk_fma_f32 v[28:29], v[22:23], v[28:29], v[140:141]
	v_lshlrev_b32_e32 v22, 16, v25
	v_and_b32_e32 v23, 0xffff0000, v25
	v_pk_add_f32 v[138:139], v[138:139], v[236:237] op_sel:[0,1] neg_lo:[0,1] neg_hi:[0,1]
	v_pk_add_f32 v[22:23], v[22:23], v[236:237] op_sel:[0,1] neg_lo:[0,1] neg_hi:[0,1]
	v_pk_mul_f32 v[138:139], v[138:139], v[238:239] op_sel_hi:[1,0]
	v_pk_mul_f32 v[22:23], v[22:23], v[238:239] op_sel_hi:[1,0]
	s_waitcnt lgkmcnt(0)
	v_pk_fma_f32 v[30:31], v[138:139], v[30:31], v[142:143]
	v_pk_fma_f32 v[32:33], v[22:23], v[32:33], v[144:145]
	v_cvt_pk_bf16_f32 v22, v26, v27
	v_cvt_pk_bf16_f32 v23, v28, v29
	v_cvt_pk_bf16_f32 v24, v30, v31
	v_cvt_pk_bf16_f32 v25, v32, v33
	v_add_u32_e32 v26, v164, v152
	ds_write_b128 v26, v[22:25]
	ds_read_b128 v[22:25], v230 offset:49184
	ds_read_b128 v[26:29], v230 offset:49200
	ds_read_b128 v[30:33], v230 offset:51232
	ds_read_b128 v[138:141], v230 offset:51248
	v_lshlrev_b32_e32 v142, 16, v10
	v_and_b32_e32 v143, 0xffff0000, v10
	v_lshlrev_b32_e32 v10, 16, v11
	v_and_b32_e32 v11, 0xffff0000, v11
	v_pk_add_f32 v[142:143], v[142:143], v[236:237] op_sel:[0,1] neg_lo:[0,1] neg_hi:[0,1]
	v_pk_add_f32 v[10:11], v[10:11], v[236:237] op_sel:[0,1] neg_lo:[0,1] neg_hi:[0,1]
	v_pk_mul_f32 v[142:143], v[142:143], v[238:239] op_sel_hi:[1,0]
	v_pk_mul_f32 v[10:11], v[10:11], v[238:239] op_sel_hi:[1,0]
	s_waitcnt lgkmcnt(1)
	v_pk_fma_f32 v[22:23], v[142:143], v[22:23], v[30:31]
	v_lshlrev_b32_e32 v30, 16, v12
	v_and_b32_e32 v31, 0xffff0000, v12
	v_pk_fma_f32 v[24:25], v[10:11], v[24:25], v[32:33]
	v_lshlrev_b32_e32 v10, 16, v13
	v_and_b32_e32 v11, 0xffff0000, v13
	v_pk_add_f32 v[30:31], v[30:31], v[236:237] op_sel:[0,1] neg_lo:[0,1] neg_hi:[0,1]
	v_pk_add_f32 v[10:11], v[10:11], v[236:237] op_sel:[0,1] neg_lo:[0,1] neg_hi:[0,1]
	v_pk_mul_f32 v[30:31], v[30:31], v[238:239] op_sel_hi:[1,0]
	v_pk_mul_f32 v[10:11], v[10:11], v[238:239] op_sel_hi:[1,0]
	s_waitcnt lgkmcnt(0)
	v_pk_fma_f32 v[26:27], v[30:31], v[26:27], v[138:139]
	v_pk_fma_f32 v[28:29], v[10:11], v[28:29], v[140:141]
	v_cvt_pk_bf16_f32 v10, v22, v23
	v_cvt_pk_bf16_f32 v11, v24, v25
	v_cvt_pk_bf16_f32 v12, v26, v27
	v_cvt_pk_bf16_f32 v13, v28, v29
	ds_write_b128 v231, v[10:13]
	ds_read_b128 v[10:13], v230 offset:49216
	ds_read_b128 v[22:25], v230 offset:49232
	ds_read_b128 v[26:29], v230 offset:51264
	ds_read_b128 v[30:33], v230 offset:51280
	v_lshlrev_b32_e32 v138, 16, v6
	v_and_b32_e32 v139, 0xffff0000, v6
	v_lshlrev_b32_e32 v6, 16, v7
	v_and_b32_e32 v7, 0xffff0000, v7
	v_pk_add_f32 v[138:139], v[138:139], v[236:237] op_sel:[0,1] neg_lo:[0,1] neg_hi:[0,1]
	v_pk_add_f32 v[6:7], v[6:7], v[236:237] op_sel:[0,1] neg_lo:[0,1] neg_hi:[0,1]
	v_pk_mul_f32 v[138:139], v[138:139], v[238:239] op_sel_hi:[1,0]
	v_pk_mul_f32 v[6:7], v[6:7], v[238:239] op_sel_hi:[1,0]
	s_waitcnt lgkmcnt(1)
	v_pk_fma_f32 v[10:11], v[138:139], v[10:11], v[26:27]
	v_lshlrev_b32_e32 v26, 16, v8
	v_and_b32_e32 v27, 0xffff0000, v8
	v_pk_fma_f32 v[12:13], v[6:7], v[12:13], v[28:29]
	v_lshlrev_b32_e32 v6, 16, v9
	v_and_b32_e32 v7, 0xffff0000, v9
	v_pk_add_f32 v[26:27], v[26:27], v[236:237] op_sel:[0,1] neg_lo:[0,1] neg_hi:[0,1]
	v_pk_add_f32 v[6:7], v[6:7], v[236:237] op_sel:[0,1] neg_lo:[0,1] neg_hi:[0,1]
	v_pk_mul_f32 v[26:27], v[26:27], v[238:239] op_sel_hi:[1,0]
	v_pk_mul_f32 v[6:7], v[6:7], v[238:239] op_sel_hi:[1,0]
	s_waitcnt lgkmcnt(0)
; #define LAS __attribute__((address_space(3)))
; DI u32x4 pk8(f32x4 a, f32x4 b) { u32x4 w; w.x = pk2(a[0], a[1]); w.y = pk2(a[2], a[3]); w.z = pk2(b[0], b[1]); w.w = pk2(b[2], b[3]); return w; }
; DI s16x4 tr_read(const LAS unsigned char* p) { return __builtin_bit_cast(s16x4, __builtin_amdgcn_ds_read_tr16_b64_v4i16((LAS v4i16_t*)p)); }
; DI void sgu_unit(const Params& p, LAS unsigned char* lds, int uid, int tid, const SguRegs& C, bool has_next, int uid_next, SguRegs& R) {
;     ...
;     const int i16 = lane & 15, qd = i16 >> 2, pp = i16 & 3, g16 = (lane >> 4) & 1;
;     f32x16 acc0, acc1;
; #pragma unroll
;     for (int r = 0; r < 16; ++r) { acc0[r] = 0.f; acc1[r] = 0.f; }
;     const LAS unsigned char* vb = lds + (8 * h + qd) * SG_STR + (64 * dh + 16 * g16 + 4 * pp) * 2;
; #pragma unroll
;     for (int js = 0; js < 8; ++js) {
;         if (js <= 2 * ib + 1) {
;             const int jb = 16 * js + 8 * h;
;             f32x4 w0 = wv[js][0], w1 = wv[js][1];
; #pragma unroll
;             for (int k = 0; k < 4; ++k) { w0[k] = (jb + k <= iloc) ? w0[k] : 0.f; w1[k] = (jb + 4 + k <= iloc) ? w1[k] : 0.f; }
;             const bf16x8 bw = __builtin_bit_cast(bf16x8, pk8(w0, w1));
;             const LAS unsigned char* va = vb + js * 16 * SG_STR;
;             { const s16x4 lo = tr_read(va), hi = tr_read(va + 4 * SG_STR); acc0 = __builtin_amdgcn_mfma_f32_32x32x16_bf16(VFR(lo, hi), bw, acc0, 0, 0, 0); }
;             { const s16x4 lo = tr_read(va + 64), hi = tr_read(va + 64 + 4 * SG_STR); acc1 = __builtin_amdgcn_mfma_f32_32x32x16_bf16(VFR(lo, hi), bw, acc1, 0, 0, 0); }
;         }
;     }
	v_pk_fma_f32 v[22:23], v[26:27], v[22:23], v[30:31]
	v_pk_fma_f32 v[24:25], v[6:7], v[24:25], v[32:33]
	v_cvt_pk_bf16_f32 v6, v10, v11
	v_cvt_pk_bf16_f32 v7, v12, v13
	v_cvt_pk_bf16_f32 v8, v22, v23
	v_cvt_pk_bf16_f32 v9, v24, v25
	ds_write_b128 v232, v[6:9]
	ds_read_b128 v[6:9], v230 offset:49248
	ds_read_b128 v[10:13], v230 offset:49264
	ds_read_b128 v[22:25], v230 offset:51296
	ds_read_b128 v[26:29], v230 offset:51312
	v_lshlrev_b32_e32 v30, 16, v2
	v_and_b32_e32 v31, 0xffff0000, v2
	v_lshlrev_b32_e32 v2, 16, v3
	v_and_b32_e32 v3, 0xffff0000, v3
	v_pk_add_f32 v[2:3], v[2:3], v[236:237] op_sel:[0,1] neg_lo:[0,1] neg_hi:[0,1]
	v_pk_add_f32 v[30:31], v[30:31], v[236:237] op_sel:[0,1] neg_lo:[0,1] neg_hi:[0,1]
	v_pk_mul_f32 v[2:3], v[2:3], v[238:239] op_sel_hi:[1,0]
	v_pk_mul_f32 v[30:31], v[30:31], v[238:239] op_sel_hi:[1,0]
	s_waitcnt lgkmcnt(1)
	v_pk_fma_f32 v[8:9], v[2:3], v[8:9], v[24:25]
	v_lshlrev_b32_e32 v2, 16, v5
	v_and_b32_e32 v3, 0xffff0000, v5
	v_pk_add_f32 v[2:3], v[2:3], v[236:237] op_sel:[0,1] neg_lo:[0,1] neg_hi:[0,1]
	v_pk_fma_f32 v[6:7], v[30:31], v[6:7], v[22:23]
	v_pk_mul_f32 v[2:3], v[2:3], v[238:239] op_sel_hi:[1,0]
	v_cmp_le_u32_e32 vcc, v157, v234
	v_lshlrev_b32_e32 v22, 16, v4
	v_and_b32_e32 v23, 0xffff0000, v4
	s_waitcnt lgkmcnt(0)
	v_pk_fma_f32 v[12:13], v[2:3], v[12:13], v[28:29]
	v_cvt_pk_bf16_f32 v2, v6, v7
	v_cndmask_b32_e32 v6, 0, v18, vcc
	v_cmp_le_u32_e32 vcc, v167, v234
	v_pk_add_f32 v[22:23], v[22:23], v[236:237] op_sel:[0,1] neg_lo:[0,1] neg_hi:[0,1]
	v_cvt_pk_bf16_f32 v3, v8, v9
	v_cndmask_b32_e32 v8, 0, v14, vcc
	v_cmp_lt_u32_e32 vcc, v157, v234
	v_pk_mul_f32 v[22:23], v[22:23], v[238:239] op_sel_hi:[1,0]
	v_cvt_pk_bf16_f32 v5, v12, v13
	v_cndmask_b32_e32 v7, 0, v19, vcc
	v_cmp_le_u32_e32 vcc, v168, v234
	v_pk_fma_f32 v[10:11], v[22:23], v[10:11], v[26:27]
	v_cvt_pk_bf16_f32 v6, v6, v7
	v_cndmask_b32_e32 v9, 0, v15, vcc
	v_cmp_le_u32_e32 vcc, v169, v234
	v_cvt_pk_bf16_f32 v4, v10, v11
	ds_write_b128 v233, v[2:5]
	v_cndmask_b32_e32 v10, 0, v20, vcc
	v_cmp_le_u32_e32 vcc, v170, v234
	v_or_b32_e32 v2, s22, v166
	v_lshlrev_b32_e32 v2, 1, v2
	v_cndmask_b32_e32 v11, 0, v16, vcc
	v_cmp_le_u32_e32 vcc, v171, v234
	v_add_u32_e32 v138, v165, v2
	s_waitcnt lgkmcnt(0)
	v_cndmask_b32_e32 v12, 0, v21, vcc
	v_cmp_le_u32_e32 vcc, v172, v234
	s_barrier
	s_nop 0
	v_cndmask_b32_e32 v13, 0, v17, vcc
	v_cmp_le_u32_e32 vcc, v173, v234
	ds_read_b64_tr_b16 v[2:3], v138
	ds_read_b64_tr_b16 v[4:5], v138 offset:1280
	v_cvt_pk_bf16_f32 v7, v10, v12
	v_cvt_pk_bf16_f32 v8, v8, v9
	v_cvt_pk_bf16_f32 v9, v11, v13
	ds_read_b64_tr_b16 v[12:13], v138 offset:1344
	ds_read_b64_tr_b16 v[10:11], v138 offset:64
	v_cndmask_b32_e32 v139, 0, v134, vcc
	v_cmp_le_u32_e32 vcc, v174, v234
	s_waitcnt lgkmcnt(2)
	v_mfma_f32_32x32x16_bf16 v[18:33], v[2:5], v[6:9], 0
	v_cndmask_b32_e32 v140, 0, v130, vcc
	v_cmp_le_u32_e32 vcc, v175, v234
	s_nop 1
	v_cndmask_b32_e32 v130, 0, v135, vcc
	v_cmp_le_u32_e32 vcc, v176, v234
	s_waitcnt lgkmcnt(0)
	v_mfma_f32_32x32x16_bf16 v[2:17], v[10:13], v[6:9], 0
	v_cvt_pk_bf16_f32 v130, v139, v130
	v_cndmask_b32_e32 v141, 0, v131, vcc
	v_cmp_le_u32_e32 vcc, v177, v234
	s_nop 1
	v_cndmask_b32_e32 v131, 0, v136, vcc
	v_cmp_le_u32_e32 vcc, v178, v234
	s_nop 1
	v_cndmask_b32_e32 v142, 0, v132, vcc
	v_cmp_le_u32_e32 vcc, v179, v234
	s_nop 1
	v_cndmask_b32_e32 v132, 0, v137, vcc
	v_cmp_le_u32_e32 vcc, v180, v234
	ds_read_b64_tr_b16 v[134:135], v138 offset:5120
	ds_read_b64_tr_b16 v[136:137], v138 offset:6400
	v_cndmask_b32_e32 v133, 0, v133, vcc
	v_cvt_pk_bf16_f32 v131, v131, v132
	v_cvt_pk_bf16_f32 v132, v140, v141
	v_cvt_pk_bf16_f32 v133, v142, v133
	ds_read_b64_tr_b16 v[142:143], v138 offset:6464
	ds_read_b64_tr_b16 v[140:141], v138 offset:5184
	s_waitcnt lgkmcnt(2)
	v_mfma_f32_32x32x16_bf16 v[18:33], v[134:137], v[130:133], v[18:33]
	s_andn2_b64 vcc, exec, s[42:43]
	s_waitcnt lgkmcnt(0)
	v_mfma_f32_32x32x16_bf16 v[2:17], v[140:143], v[130:133], v[2:17]
	s_cbranch_vccnz .LBB0_1254
	v_cmp_le_u32_e32 vcc, v181, v234
	s_nop 1
	v_cndmask_b32_e32 v130, 0, v126, vcc
	v_cmp_le_u32_e32 vcc, v182, v234
	s_nop 1
	v_cndmask_b32_e32 v131, 0, v118, vcc
	v_cmp_le_u32_e32 vcc, v183, v234
	s_nop 1
	v_cndmask_b32_e32 v118, 0, v127, vcc
	v_cmp_le_u32_e32 vcc, v184, v234
	v_cvt_pk_bf16_f32 v118, v130, v118
	s_nop 0
	v_cndmask_b32_e32 v132, 0, v119, vcc
	v_cmp_le_u32_e32 vcc, v185, v234
	s_nop 1
	v_cndmask_b32_e32 v119, 0, v128, vcc
	v_cmp_le_u32_e32 vcc, v186, v234
	s_nop 1
	v_cndmask_b32_e32 v133, 0, v120, vcc
	v_cmp_le_u32_e32 vcc, v187, v234
	s_nop 1
	v_cndmask_b32_e32 v120, 0, v129, vcc
	v_cmp_le_u32_e32 vcc, v188, v234
	ds_read_b64_tr_b16 v[126:127], v138 offset:10240
	ds_read_b64_tr_b16 v[128:129], v138 offset:11520
	v_cndmask_b32_e32 v121, 0, v121, vcc
	v_cvt_pk_bf16_f32 v119, v119, v120
	v_cvt_pk_bf16_f32 v120, v131, v132
	v_cvt_pk_bf16_f32 v121, v133, v121
	ds_read_b64_tr_b16 v[132:133], v138 offset:11584
	ds_read_b64_tr_b16 v[130:131], v138 offset:10304
	s_waitcnt lgkmcnt(2)
	v_mfma_f32_32x32x16_bf16 v[18:33], v[126:129], v[118:121], v[18:33]
	s_waitcnt lgkmcnt(0)
	v_mfma_f32_32x32x16_bf16 v[2:17], v[130:133], v[118:121], v[2:17]
